# adds: softmax row-sum and bias v_pk_add_f32 in the prompt attention tile loops split into scalar v_add_f32 pairs (bit-identical)
# speedup vs baseline: 1.0005x; 1.0005x over previous
; __device__ __forceinline__ int crow(int r, int hi) { return (r & 3) + 8 * (r >> 2) + 4 * hi; }
; template <int DQK, int DV, bool HAS_BIAS>
; __device__ __forceinline__ void attn_tile(AttnState<DQK, DV>& st, const LAS unsigned char* Kt, const LAS unsigned char* Vt, int bias_mode, const LAS float* tab, int rel0, int nkeys, bool first, LAS float* wsf, int lane) {
;     ...
;     if (HAS_BIAS && bias_mode == 2) {
;         asm volatile("" ::: "memory");
; #pragma unroll
;         for (int r = 0; r < 16; ++r) {
;             const int k = crow(r, hi);
;             const int i0 = min(max(rel0 + k + 128, 0), 191), i1 = min(max(rel0 + k + 160, 0), 191);
;             p0[r] = tab[i0] + st.negm[r]; p1[r] = tab[i1] + st.negm[r];
;         }
;         p0 = __builtin_amdgcn_mfma_f32_32x32x16_bf16(ka[0], st.qf[0], p0, 0, 0, 0);
;         p1 = __builtin_amdgcn_mfma_f32_32x32x16_bf16(kb[0], st.qf[0], p1, 0, 0, 0);
.LBB0_525:
	s_andn2_b64 vcc, exec, s[2:3]
	s_cbranch_vccnz .LBB0_527
	s_nop 6
	v_lshl_add_u32 v224, s58, 2, v225
	ds_read_b32 v80, v224 offset:0
	ds_read_b32 v96, v224 offset:128
	ds_read_b32 v81, v224 offset:4
	ds_read_b32 v97, v224 offset:132
	ds_read_b32 v82, v224 offset:8
	ds_read_b32 v98, v224 offset:136
	ds_read_b32 v83, v224 offset:12
	ds_read_b32 v99, v224 offset:140
	ds_read_b32 v84, v224 offset:32
	ds_read_b32 v100, v224 offset:160
	ds_read_b32 v85, v224 offset:36
	ds_read_b32 v101, v224 offset:164
	ds_read_b32 v86, v224 offset:40
	ds_read_b32 v102, v224 offset:168
	ds_read_b32 v87, v224 offset:44
	ds_read_b32 v103, v224 offset:172
	ds_read_b32 v88, v224 offset:64
	ds_read_b32 v104, v224 offset:192
	ds_read_b32 v89, v224 offset:68
	ds_read_b32 v105, v224 offset:196
	ds_read_b32 v90, v224 offset:72
	ds_read_b32 v106, v224 offset:200
	ds_read_b32 v91, v224 offset:76
	ds_read_b32 v107, v224 offset:204
	ds_read_b32 v92, v224 offset:96
	ds_read_b32 v108, v224 offset:224
	ds_read_b32 v93, v224 offset:100
	ds_read_b32 v109, v224 offset:228
	ds_read_b32 v94, v224 offset:104
	ds_read_b32 v110, v224 offset:232
	ds_read_b32 v95, v224 offset:108
	ds_read_b32 v111, v224 offset:236
	s_waitcnt lgkmcnt(0)
	v_add_f32_e32 v94, v78, v94
	v_add_f32_e32 v95, v79, v95
	s_waitcnt lgkmcnt(3)
	v_add_f32_e32 v92, v76, v92
	v_add_f32_e32 v93, v77, v93
	v_add_f32_e32 v90, v74, v90
	v_add_f32_e32 v91, v75, v91
	v_add_f32_e32 v88, v72, v88
	v_add_f32_e32 v89, v73, v89
	v_add_f32_e32 v86, v70, v86
	v_add_f32_e32 v87, v71, v87
	v_add_f32_e32 v84, v68, v84
	v_add_f32_e32 v85, v69, v85
	v_add_f32_e32 v82, v66, v82
	v_add_f32_e32 v83, v67, v83
	v_add_f32_e32 v80, v64, v80
	v_add_f32_e32 v81, v65, v81
	s_waitcnt lgkmcnt(1)
	v_add_f32_e32 v110, v78, v110
	v_add_f32_e32 v111, v79, v111
	s_waitcnt lgkmcnt(0)
	v_add_f32_e32 v108, v76, v108
	v_add_f32_e32 v109, v77, v109
	v_add_f32_e32 v106, v74, v106
	v_add_f32_e32 v107, v75, v107
	v_add_f32_e32 v104, v72, v104
	v_add_f32_e32 v105, v73, v105
	v_add_f32_e32 v102, v70, v102
	v_add_f32_e32 v103, v71, v103
	v_add_f32_e32 v100, v68, v100
	v_add_f32_e32 v101, v69, v101
	v_add_f32_e32 v98, v66, v98
	v_add_f32_e32 v99, v67, v99
	v_add_f32_e32 v96, v64, v96
	v_add_f32_e32 v97, v65, v97
	s_waitcnt vmcnt(6)
	v_mfma_f32_32x32x16_bf16 v[80:95], v[180:183], v[112:115], v[80:95]
	v_mfma_f32_32x32x16_bf16 v[96:111], v[176:179], v[112:115], v[96:111]

; template <int DQK, int DV, bool HAS_BIAS>
; __device__ __forceinline__ void attn_tile(AttnState<DQK, DV>& st, const LAS unsigned char* Kt, const LAS unsigned char* Vt, int bias_mode, const LAS float* tab, int rel0, int nkeys, bool first, LAS float* wsf, int lane) {
;     ...
;     float sum0 = 0.f, sum1 = 0.f;
; #pragma unroll
;     for (int r = 0; r < 16; ++r) { p0[r] = __builtin_amdgcn_exp2f(p0[r]); p1[r] = __builtin_amdgcn_exp2f(p1[r]); sum0 += p0[r]; sum1 += p1[r]; }
;     st.l += sum0 + sum1;
;     bf16x8 pf[4];
;     pf[0] = pack8(p0[0], p0[1], p0[2], p0[3], p0[4], p0[5], p0[6], p0[7]);
;     pf[1] = pack8(p0[8], p0[9], p0[10], p0[11], p0[12], p0[13], p0[14], p0[15]);
;     pf[2] = pack8(p1[0], p1[1], p1[2], p1[3], p1[4], p1[5], p1[6], p1[7]);
;     pf[3] = pack8(p1[8], p1[9], p1[10], p1[11], p1[12], p1[13], p1[14], p1[15]);
.LBB0_535:
	v_exp_f32_e32 v169, v80
	v_exp_f32_e32 v168, v96
	v_exp_f32_e32 v171, v81
	v_exp_f32_e32 v170, v97
	v_exp_f32_e32 v97, v82
	v_exp_f32_e32 v96, v98
	v_exp_f32_e32 v173, v83
	v_exp_f32_e32 v172, v99
	v_add_f32_e32 v80, 0, v168
	v_add_f32_e32 v81, 0, v169
	v_exp_f32_e32 v99, v84
	v_exp_f32_e32 v98, v100
	v_add_f32_e32 v80, v170, v80
	v_add_f32_e32 v81, v171, v81
	v_exp_f32_e32 v175, v85
	v_exp_f32_e32 v174, v101
	v_add_f32_e32 v80, v96, v80
	v_add_f32_e32 v81, v97, v81
	v_exp_f32_e32 v101, v86
	v_exp_f32_e32 v100, v102
	v_add_f32_e32 v80, v172, v80
	v_add_f32_e32 v81, v173, v81
	v_exp_f32_e32 v177, v87
	v_exp_f32_e32 v176, v103
	v_exp_f32_e32 v103, v88
	v_exp_f32_e32 v102, v104
	v_add_f32_e32 v80, v98, v80
	v_add_f32_e32 v81, v99, v81
	v_exp_f32_e32 v179, v89
	v_exp_f32_e32 v178, v105
	v_add_f32_e32 v80, v174, v80
	v_add_f32_e32 v81, v175, v81
	v_exp_f32_e32 v105, v90
	v_exp_f32_e32 v104, v106
	v_add_f32_e32 v80, v100, v80
	v_add_f32_e32 v81, v101, v81
	v_exp_f32_e32 v181, v91
	v_exp_f32_e32 v180, v107
	v_add_f32_e32 v80, v176, v80
	v_add_f32_e32 v81, v177, v81
	v_exp_f32_e32 v107, v92
	v_exp_f32_e32 v106, v108
	v_add_f32_e32 v80, v102, v80
	v_add_f32_e32 v81, v103, v81
	v_exp_f32_e32 v183, v93
	v_exp_f32_e32 v182, v109
	v_add_f32_e32 v80, v178, v80
	v_add_f32_e32 v81, v179, v81
	v_exp_f32_e32 v109, v94
	v_exp_f32_e32 v108, v110
	v_add_f32_e32 v80, v104, v80
	v_add_f32_e32 v81, v105, v81
	v_exp_f32_e32 v223, v95
	v_exp_f32_e32 v222, v111
	v_add_f32_e32 v80, v180, v80
	v_add_f32_e32 v81, v181, v81
	v_cvt_pk_bf16_f32 v82, v99, v175
	v_add_f32_e32 v80, v106, v80
	v_add_f32_e32 v81, v107, v81
	v_cvt_pk_bf16_f32 v83, v101, v177
	v_add_f32_e32 v80, v182, v80
	v_add_f32_e32 v81, v183, v81
	v_cvt_pk_bf16_f32 v84, v103, v179
	v_add_f32_e32 v80, v108, v80
	v_add_f32_e32 v81, v109, v81
	v_cvt_pk_bf16_f32 v85, v105, v181
	v_add_f32_e32 v80, v222, v80
	v_add_f32_e32 v81, v223, v81
	v_cvt_pk_bf16_f32 v86, v107, v183
	v_add_f32_e32 v80, v80, v81
	v_add_f32_e32 v184, v184, v80
	v_cvt_pk_bf16_f32 v80, v169, v171
	v_cvt_pk_bf16_f32 v81, v97, v173
	v_cvt_pk_bf16_f32 v87, v109, v223
	v_cvt_pk_bf16_f32 v88, v168, v170
	v_cvt_pk_bf16_f32 v89, v96, v172
	v_cvt_pk_bf16_f32 v90, v98, v174
	v_cvt_pk_bf16_f32 v91, v100, v176
	v_cvt_pk_bf16_f32 v92, v102, v178
	v_cvt_pk_bf16_f32 v93, v104, v180
	v_cvt_pk_bf16_f32 v94, v106, v182
	v_cvt_pk_bf16_f32 v95, v108, v222
	s_waitcnt lgkmcnt(2)
	v_mfma_f32_32x32x16_bf16 v[48:63], v[80:83], v[164:167], v[48:63]
	ds_read_b64_tr_b16 v[96:97], v217 offset:22592
	ds_read_b64_tr_b16 v[98:99], v217 offset:25152
	ds_read_b64_tr_b16 v[100:101], v217 offset:27712
	ds_read_b64_tr_b16 v[102:103], v217 offset:30272
	ds_read_b64_tr_b16 v[104:105], v217 offset:17472
	ds_read_b64_tr_b16 v[106:107], v217 offset:20032
	ds_read_b64_tr_b16 v[108:109], v217 offset:32832
	ds_read_b64_tr_b16 v[110:111], v217 offset:35392
	v_mfma_f32_32x32x16_bf16 v[48:63], v[84:87], v[160:163], v[48:63]
	v_mfma_f32_32x32x16_bf16 v[48:63], v[88:91], v[156:159], v[48:63]
	s_waitcnt lgkmcnt(8)
	v_mfma_f32_32x32x16_bf16 v[48:63], v[92:95], v[152:155], v[48:63]
	s_waitcnt lgkmcnt(2)
	v_mfma_f32_32x32x16_bf16 v[32:47], v[80:83], v[104:107], v[32:47]
	v_mfma_f32_32x32x16_bf16 v[32:47], v[84:87], v[96:99], v[32:47]
	v_mfma_f32_32x32x16_bf16 v[32:47], v[88:91], v[100:103], v[32:47]
	ds_read_b64_tr_b16 v[96:97], v217 offset:22656
	ds_read_b64_tr_b16 v[98:99], v217 offset:25216
	ds_read_b64_tr_b16 v[100:101], v217 offset:27776
	ds_read_b64_tr_b16 v[102:103], v217 offset:30336
	ds_read_b64_tr_b16 v[104:105], v217 offset:17536
	ds_read_b64_tr_b16 v[106:107], v217 offset:20096
	ds_read_b64_tr_b16 v[152:153], v217 offset:32896
	ds_read_b64_tr_b16 v[154:155], v217 offset:35456
	s_waitcnt lgkmcnt(8)
	v_mfma_f32_32x32x16_bf16 v[32:47], v[92:95], v[108:111], v[32:47]
	s_waitcnt lgkmcnt(2)
	v_mfma_f32_32x32x16_bf16 v[16:31], v[80:83], v[104:107], v[16:31]
	v_mfma_f32_32x32x16_bf16 v[16:31], v[84:87], v[96:99], v[16:31]
	v_mfma_f32_32x32x16_bf16 v[16:31], v[88:91], v[100:103], v[16:31]
	ds_read_b64_tr_b16 v[96:97], v217 offset:22720
	ds_read_b64_tr_b16 v[98:99], v217 offset:25280
	ds_read_b64_tr_b16 v[100:101], v217 offset:27840
	ds_read_b64_tr_b16 v[102:103], v217 offset:30400
	ds_read_b64_tr_b16 v[104:105], v217 offset:17600
	ds_read_b64_tr_b16 v[106:107], v217 offset:20160
	ds_read_b64_tr_b16 v[108:109], v217 offset:32960
	ds_read_b64_tr_b16 v[110:111], v217 offset:35520
	s_waitcnt lgkmcnt(8)
	v_mfma_f32_32x32x16_bf16 v[16:31], v[92:95], v[152:155], v[16:31]
	s_waitcnt lgkmcnt(2)
	v_mfma_f32_32x32x16_bf16 v[0:15], v[80:83], v[104:107], v[0:15]
	v_mfma_f32_32x32x16_bf16 v[0:15], v[84:87], v[96:99], v[0:15]
	v_mfma_f32_32x32x16_bf16 v[0:15], v[88:91], v[100:103], v[0:15]
	s_waitcnt lgkmcnt(0)
	v_mfma_f32_32x32x16_bf16 v[0:15], v[92:95], v[108:111], v[0:15]

; __device__ __forceinline__ int crow(int r, int hi) { return (r & 3) + 8 * (r >> 2) + 4 * hi; }
; template <int DQK, int DV, bool HAS_BIAS>
; __device__ __forceinline__ void attn_tile(AttnState<DQK, DV>& st, const LAS unsigned char* Kt, const LAS unsigned char* Vt, int bias_mode, const LAS float* tab, int rel0, int nkeys, bool first, LAS float* wsf, int lane) {
;     ...
;     if (HAS_BIAS && bias_mode == 2) {
;         asm volatile("" ::: "memory");
; #pragma unroll
;         for (int r = 0; r < 16; ++r) {
;             const int k = crow(r, hi);
;             const int i0 = min(max(rel0 + k + 128, 0), 191), i1 = min(max(rel0 + k + 160, 0), 191);
;             p0[r] = tab[i0] + st.negm[r]; p1[r] = tab[i1] + st.negm[r];
;         }
;         p0 = __builtin_amdgcn_mfma_f32_32x32x16_bf16(ka[0], st.qf[0], p0, 0, 0, 0);
;         p1 = __builtin_amdgcn_mfma_f32_32x32x16_bf16(kb[0], st.qf[0], p1, 0, 0, 0);
.LBB0_545:
	s_andn2_b64 vcc, exec, s[2:3]
	s_cbranch_vccnz .LBB0_547
	s_nop 6
	v_lshl_add_u32 v224, s58, 2, v225
	ds_read_b32 v80, v224 offset:256
	ds_read_b32 v96, v224 offset:384
	ds_read_b32 v81, v224 offset:260
	ds_read_b32 v97, v224 offset:388
	ds_read_b32 v82, v224 offset:264
	ds_read_b32 v98, v224 offset:392
	ds_read_b32 v83, v224 offset:268
	ds_read_b32 v99, v224 offset:396
	ds_read_b32 v84, v224 offset:288
	ds_read_b32 v100, v224 offset:416
	ds_read_b32 v85, v224 offset:292
	ds_read_b32 v101, v224 offset:420
	ds_read_b32 v86, v224 offset:296
	ds_read_b32 v102, v224 offset:424
	ds_read_b32 v87, v224 offset:300
	ds_read_b32 v103, v224 offset:428
	ds_read_b32 v88, v224 offset:320
	ds_read_b32 v104, v224 offset:448
	ds_read_b32 v89, v224 offset:324
	ds_read_b32 v105, v224 offset:452
	ds_read_b32 v90, v224 offset:328
	ds_read_b32 v106, v224 offset:456
	ds_read_b32 v91, v224 offset:332
	ds_read_b32 v107, v224 offset:460
	ds_read_b32 v92, v224 offset:352
	ds_read_b32 v108, v224 offset:480
	ds_read_b32 v93, v224 offset:356
	ds_read_b32 v109, v224 offset:484
	ds_read_b32 v94, v224 offset:360
	ds_read_b32 v110, v224 offset:488
	ds_read_b32 v95, v224 offset:364
	ds_read_b32 v111, v224 offset:492
	s_waitcnt lgkmcnt(0)
	v_add_f32_e32 v94, v78, v94
	v_add_f32_e32 v95, v79, v95
	s_waitcnt lgkmcnt(3)
	v_add_f32_e32 v92, v76, v92
	v_add_f32_e32 v93, v77, v93
	v_add_f32_e32 v90, v74, v90
	v_add_f32_e32 v91, v75, v91
	v_add_f32_e32 v88, v72, v88
	v_add_f32_e32 v89, v73, v89
	v_add_f32_e32 v86, v70, v86
	v_add_f32_e32 v87, v71, v87
	v_add_f32_e32 v84, v68, v84
	v_add_f32_e32 v85, v69, v85
	v_add_f32_e32 v82, v66, v82
	v_add_f32_e32 v83, v67, v83
	v_add_f32_e32 v80, v64, v80
	v_add_f32_e32 v81, v65, v81
	s_waitcnt lgkmcnt(1)
	v_add_f32_e32 v110, v78, v110
	v_add_f32_e32 v111, v79, v111
	s_waitcnt lgkmcnt(0)
	v_add_f32_e32 v108, v76, v108
	v_add_f32_e32 v109, v77, v109
	v_add_f32_e32 v106, v74, v106
	v_add_f32_e32 v107, v75, v107
	v_add_f32_e32 v104, v72, v104
	v_add_f32_e32 v105, v73, v105
	v_add_f32_e32 v102, v70, v102
	v_add_f32_e32 v103, v71, v103
	v_add_f32_e32 v100, v68, v100
	v_add_f32_e32 v101, v69, v101
	v_add_f32_e32 v98, v66, v98
	v_add_f32_e32 v99, v67, v99
	v_add_f32_e32 v96, v64, v96
	v_add_f32_e32 v97, v65, v97
	v_mfma_f32_32x32x16_bf16 v[80:95], v[180:183], v[112:115], v[80:95]
	s_nop 0
	v_mfma_f32_32x32x16_bf16 v[96:111], v[176:179], v[112:115], v[96:111]

; __device__ __forceinline__ s16x4 vtr(const LAS unsigned char* p) { return __builtin_bit_cast(s16x4, __builtin_amdgcn_ds_read_tr16_b64_v4i16((LAS v4i16_t*)p)); }
; template <int DQK, int DV, bool HAS_BIAS>
; __device__ __forceinline__ void attn_tile(AttnState<DQK, DV>& st, const LAS unsigned char* Kt, const LAS unsigned char* Vt, int bias_mode, const LAS float* tab, int rel0, int nkeys, bool first, LAS float* wsf, int lane) {
;     ...
;     float sum0 = 0.f, sum1 = 0.f;
; #pragma unroll
;     for (int r = 0; r < 16; ++r) { p0[r] = __builtin_amdgcn_exp2f(p0[r]); p1[r] = __builtin_amdgcn_exp2f(p1[r]); sum0 += p0[r]; sum1 += p1[r]; }
;     st.l += sum0 + sum1;
;     bf16x8 pf[4];
;     pf[0] = pack8(p0[0], p0[1], p0[2], p0[3], p0[4], p0[5], p0[6], p0[7]);
;     pf[1] = pack8(p0[8], p0[9], p0[10], p0[11], p0[12], p0[13], p0[14], p0[15]);
;     pf[2] = pack8(p1[0], p1[1], p1[2], p1[3], p1[4], p1[5], p1[6], p1[7]);
;     pf[3] = pack8(p1[8], p1[9], p1[10], p1[11], p1[12], p1[13], p1[14], p1[15]);
;     __builtin_amdgcn_sched_barrier(0);
; #pragma unroll
;     for (int db = 0; db < NDB; ++db) {
;         if (db + 1 < NDB) {
; #pragma unroll
;             for (int s4 = 0; s4 < 4; ++s4) { vlo[(db + 1) & 1][s4] = vtr(vp + (16 * s4) * PV + (db + 1) * 64); vhi[(db + 1) & 1][s4] = vtr(vp + (16 * s4 + 8) * PV + (db + 1) * 64); }
;         }
; #pragma unroll
;         for (int s4 = 0; s4 < 4; ++s4) {
;             const s16x4 lo = vlo[db & 1][s4], h4 = vhi[db & 1][s4];
;             const bf16x8 vb = {lo[0], lo[1], lo[2], lo[3], h4[0], h4[1], h4[2], h4[3]};
;             st.o[db] = __builtin_amdgcn_mfma_f32_32x32x16_bf16(pf[s4], vb, st.o[db], 0, 0, 0);
;         }
;         __builtin_amdgcn_sched_barrier(0);
;     }
.LBB0_551:
	v_exp_f32_e32 v169, v80
	v_exp_f32_e32 v168, v96
	v_exp_f32_e32 v171, v81
	v_exp_f32_e32 v170, v97
	v_exp_f32_e32 v97, v82
	v_exp_f32_e32 v96, v98
	v_exp_f32_e32 v173, v83
	v_exp_f32_e32 v172, v99
	v_add_f32_e32 v80, 0, v168
	v_add_f32_e32 v81, 0, v169
	v_exp_f32_e32 v99, v84
	v_exp_f32_e32 v98, v100
	v_add_f32_e32 v80, v170, v80
	v_add_f32_e32 v81, v171, v81
	v_exp_f32_e32 v175, v85
	v_exp_f32_e32 v174, v101
	v_add_f32_e32 v80, v96, v80
	v_add_f32_e32 v81, v97, v81
	v_exp_f32_e32 v101, v86
	v_exp_f32_e32 v100, v102
	v_add_f32_e32 v80, v172, v80
	v_add_f32_e32 v81, v173, v81
	v_exp_f32_e32 v177, v87
	v_exp_f32_e32 v176, v103
	v_exp_f32_e32 v103, v88
	v_exp_f32_e32 v102, v104
	v_add_f32_e32 v80, v98, v80
	v_add_f32_e32 v81, v99, v81
	v_exp_f32_e32 v179, v89
	v_exp_f32_e32 v178, v105
	v_add_f32_e32 v80, v174, v80
	v_add_f32_e32 v81, v175, v81
	v_exp_f32_e32 v105, v90
	v_exp_f32_e32 v104, v106
	v_add_f32_e32 v80, v100, v80
	v_add_f32_e32 v81, v101, v81
	v_exp_f32_e32 v181, v91
	v_exp_f32_e32 v180, v107
	v_add_f32_e32 v80, v176, v80
	v_add_f32_e32 v81, v177, v81
	v_exp_f32_e32 v107, v92
	v_exp_f32_e32 v106, v108
	v_add_f32_e32 v80, v102, v80
	v_add_f32_e32 v81, v103, v81
	v_exp_f32_e32 v183, v93
	v_exp_f32_e32 v182, v109
	v_add_f32_e32 v80, v178, v80
	v_add_f32_e32 v81, v179, v81
	v_exp_f32_e32 v109, v94
	v_exp_f32_e32 v108, v110
	v_add_f32_e32 v80, v104, v80
	v_add_f32_e32 v81, v105, v81
	v_exp_f32_e32 v201, v95
	v_exp_f32_e32 v200, v111
	v_add_f32_e32 v80, v180, v80
	v_add_f32_e32 v81, v181, v81
	v_cvt_pk_bf16_f32 v82, v99, v175
	v_add_f32_e32 v80, v106, v80
	v_add_f32_e32 v81, v107, v81
	v_cvt_pk_bf16_f32 v83, v101, v177
	v_add_f32_e32 v80, v182, v80
	v_add_f32_e32 v81, v183, v81
	v_cvt_pk_bf16_f32 v84, v103, v179
	v_add_f32_e32 v80, v108, v80
	v_add_f32_e32 v81, v109, v81
	v_cvt_pk_bf16_f32 v85, v105, v181
	v_add_f32_e32 v80, v200, v80
	v_add_f32_e32 v81, v201, v81
	v_cvt_pk_bf16_f32 v86, v107, v183
	v_add_f32_e32 v80, v80, v81
	v_add_f32_e32 v184, v184, v80
	v_cvt_pk_bf16_f32 v80, v169, v171
	v_cvt_pk_bf16_f32 v81, v97, v173
	v_cvt_pk_bf16_f32 v87, v109, v201
	v_cvt_pk_bf16_f32 v88, v168, v170
	v_cvt_pk_bf16_f32 v89, v96, v172
	v_cvt_pk_bf16_f32 v90, v98, v174
	v_cvt_pk_bf16_f32 v91, v100, v176
	v_cvt_pk_bf16_f32 v92, v102, v178
	v_cvt_pk_bf16_f32 v93, v104, v180
	v_cvt_pk_bf16_f32 v94, v106, v182
	v_cvt_pk_bf16_f32 v95, v108, v200
	s_waitcnt lgkmcnt(6)
	v_mfma_f32_32x32x16_bf16 v[48:63], v[80:83], v[164:167], v[48:63]
	ds_read_b64_tr_b16 v[96:97], v217 offset:47168
	ds_read_b64_tr_b16 v[98:99], v217 offset:49728
	ds_read_b64_tr_b16 v[100:101], v217 offset:52288
	ds_read_b64_tr_b16 v[102:103], v217 offset:54848
	ds_read_b64_tr_b16 v[104:105], v217 offset:57408
	ds_read_b64_tr_b16 v[106:107], v217 offset:59968
	ds_read_b64_tr_b16 v[108:109], v217 offset:62528
	ds_read_b64_tr_b16 v[110:111], v217 offset:65088
	s_waitcnt lgkmcnt(12)
	v_mfma_f32_32x32x16_bf16 v[48:63], v[84:87], v[160:163], v[48:63]
	s_waitcnt lgkmcnt(10)
	v_mfma_f32_32x32x16_bf16 v[48:63], v[88:91], v[156:159], v[48:63]
	s_waitcnt lgkmcnt(8)
	v_mfma_f32_32x32x16_bf16 v[48:63], v[92:95], v[152:155], v[48:63]
	s_waitcnt lgkmcnt(6)
	v_mfma_f32_32x32x16_bf16 v[32:47], v[80:83], v[96:99], v[32:47]
	s_waitcnt lgkmcnt(4)
	v_mfma_f32_32x32x16_bf16 v[32:47], v[84:87], v[100:103], v[32:47]
	s_waitcnt lgkmcnt(2)
	v_mfma_f32_32x32x16_bf16 v[32:47], v[88:91], v[104:107], v[32:47]
	ds_read_b64_tr_b16 v[96:97], v217 offset:47232
	ds_read_b64_tr_b16 v[98:99], v217 offset:49792
	ds_read_b64_tr_b16 v[100:101], v217 offset:52352
	ds_read_b64_tr_b16 v[102:103], v217 offset:54912
	ds_read_b64_tr_b16 v[104:105], v217 offset:57472
	ds_read_b64_tr_b16 v[106:107], v217 offset:60032
	ds_read_b64_tr_b16 v[152:153], v217 offset:62592
	ds_read_b64_tr_b16 v[154:155], v217 offset:65152
	s_waitcnt lgkmcnt(8)
	v_mfma_f32_32x32x16_bf16 v[32:47], v[92:95], v[108:111], v[32:47]
	s_waitcnt lgkmcnt(6)
	v_mfma_f32_32x32x16_bf16 v[16:31], v[80:83], v[96:99], v[16:31]
	s_waitcnt lgkmcnt(4)
	v_mfma_f32_32x32x16_bf16 v[16:31], v[84:87], v[100:103], v[16:31]
	s_waitcnt lgkmcnt(2)
	v_mfma_f32_32x32x16_bf16 v[16:31], v[88:91], v[104:107], v[16:31]
	ds_read_b64_tr_b16 v[96:97], v217 offset:47296
	ds_read_b64_tr_b16 v[98:99], v217 offset:49856
	ds_read_b64_tr_b16 v[100:101], v217 offset:52416
	ds_read_b64_tr_b16 v[102:103], v217 offset:54976
	ds_read_b64_tr_b16 v[104:105], v217 offset:57536
	ds_read_b64_tr_b16 v[106:107], v217 offset:60096
	ds_read_b64_tr_b16 v[108:109], v217 offset:62656
	ds_read_b64_tr_b16 v[110:111], v217 offset:65216
	s_waitcnt lgkmcnt(8)
	v_mfma_f32_32x32x16_bf16 v[16:31], v[92:95], v[152:155], v[16:31]
	s_waitcnt lgkmcnt(6)
	v_mfma_f32_32x32x16_bf16 v[0:15], v[80:83], v[96:99], v[0:15]
	s_waitcnt lgkmcnt(4)
	v_mfma_f32_32x32x16_bf16 v[0:15], v[84:87], v[100:103], v[0:15]
	s_waitcnt lgkmcnt(2)
	v_mfma_f32_32x32x16_bf16 v[0:15], v[88:91], v[104:107], v[0:15]
	s_waitcnt lgkmcnt(0)
	v_mfma_f32_32x32x16_bf16 v[0:15], v[92:95], v[108:111], v[0:15]
	s_andn2_b64 vcc, exec, s[42:43]
	s_cbranch_vccz .LBB0_539
	s_branch .LBB0_540

; template <int DQK, int DV, bool HAS_BIAS>
; __device__ __forceinline__ void attn_tile(AttnState<DQK, DV>& st, const LAS unsigned char* Kt, const LAS unsigned char* Vt, int bias_mode, const LAS float* tab, int rel0, int nkeys, bool first, LAS float* wsf, int lane) {
;     ...
;     float sum0 = 0.f, sum1 = 0.f;
; #pragma unroll
;     for (int r = 0; r < 16; ++r) { p0[r] = __builtin_amdgcn_exp2f(p0[r]); p1[r] = __builtin_amdgcn_exp2f(p1[r]); sum0 += p0[r]; sum1 += p1[r]; }
;     st.l += sum0 + sum1;
;     bf16x8 pf[4];
;     pf[0] = pack8(p0[0], p0[1], p0[2], p0[3], p0[4], p0[5], p0[6], p0[7]);
;     pf[1] = pack8(p0[8], p0[9], p0[10], p0[11], p0[12], p0[13], p0[14], p0[15]);
;     pf[2] = pack8(p1[0], p1[1], p1[2], p1[3], p1[4], p1[5], p1[6], p1[7]);
;     pf[3] = pack8(p1[8], p1[9], p1[10], p1[11], p1[12], p1[13], p1[14], p1[15]);
.LBB0_589:
	v_exp_f32_e32 v151, v48
	v_exp_f32_e32 v150, v64
	v_exp_f32_e32 v165, v49
	v_exp_f32_e32 v164, v65
	v_exp_f32_e32 v65, v50
	v_exp_f32_e32 v64, v66
	v_exp_f32_e32 v167, v51
	v_exp_f32_e32 v166, v67
	v_add_f32_e32 v48, 0, v150
	v_add_f32_e32 v49, 0, v151
	v_exp_f32_e32 v67, v52
	v_exp_f32_e32 v66, v68
	v_add_f32_e32 v48, v164, v48
	v_add_f32_e32 v49, v165, v49
	v_exp_f32_e32 v169, v53
	v_exp_f32_e32 v168, v69
	v_add_f32_e32 v48, v64, v48
	v_add_f32_e32 v49, v65, v49
	v_exp_f32_e32 v69, v54
	v_exp_f32_e32 v68, v70
	v_add_f32_e32 v48, v166, v48
	v_add_f32_e32 v49, v167, v49
	v_exp_f32_e32 v171, v55
	v_exp_f32_e32 v170, v71
	v_exp_f32_e32 v71, v56
	v_exp_f32_e32 v70, v72
	v_add_f32_e32 v48, v66, v48
	v_add_f32_e32 v49, v67, v49
	v_exp_f32_e32 v173, v57
	v_exp_f32_e32 v172, v73
	v_add_f32_e32 v48, v168, v48
	v_add_f32_e32 v49, v169, v49
	v_exp_f32_e32 v73, v58
	v_exp_f32_e32 v72, v74
	v_add_f32_e32 v48, v68, v48
	v_add_f32_e32 v49, v69, v49
	v_exp_f32_e32 v175, v59
	v_exp_f32_e32 v174, v75
	v_add_f32_e32 v48, v170, v48
	v_add_f32_e32 v49, v171, v49
	v_exp_f32_e32 v75, v60
	v_exp_f32_e32 v74, v76
	v_add_f32_e32 v48, v70, v48
	v_add_f32_e32 v49, v71, v49
	v_exp_f32_e32 v177, v61
	v_exp_f32_e32 v176, v77
	v_add_f32_e32 v48, v172, v48
	v_add_f32_e32 v49, v173, v49
	v_exp_f32_e32 v77, v62
	v_exp_f32_e32 v76, v78
	v_add_f32_e32 v48, v72, v48
	v_add_f32_e32 v49, v73, v49
	v_exp_f32_e32 v179, v63
	v_exp_f32_e32 v178, v79
	v_add_f32_e32 v48, v174, v48
	v_add_f32_e32 v49, v175, v49
	v_cvt_pk_bf16_f32 v50, v67, v169
	v_add_f32_e32 v48, v74, v48
	v_add_f32_e32 v49, v75, v49
	v_cvt_pk_bf16_f32 v51, v69, v171
	v_add_f32_e32 v48, v176, v48
	v_add_f32_e32 v49, v177, v49
	v_cvt_pk_bf16_f32 v52, v71, v173
	v_add_f32_e32 v48, v76, v48
	v_add_f32_e32 v49, v77, v49
	v_cvt_pk_bf16_f32 v53, v73, v175
	v_add_f32_e32 v48, v178, v48
	v_add_f32_e32 v49, v179, v49
	v_cvt_pk_bf16_f32 v54, v75, v177
	v_add_f32_e32 v48, v48, v49
	v_add_f32_e32 v160, v160, v48
	v_cvt_pk_bf16_f32 v48, v151, v165
	v_cvt_pk_bf16_f32 v49, v65, v167
	v_cvt_pk_bf16_f32 v55, v77, v179
	v_cvt_pk_bf16_f32 v56, v150, v164
	v_cvt_pk_bf16_f32 v57, v64, v166
	v_cvt_pk_bf16_f32 v58, v66, v168
	v_cvt_pk_bf16_f32 v59, v68, v170
	v_cvt_pk_bf16_f32 v60, v70, v172
	v_cvt_pk_bf16_f32 v61, v72, v174
	v_cvt_pk_bf16_f32 v62, v74, v176
	v_cvt_pk_bf16_f32 v63, v76, v178
	s_waitcnt lgkmcnt(6)
	v_mfma_f32_32x32x16_bf16 v[16:31], v[48:51], v[140:143], v[16:31]
	ds_read_b64_tr_b16 v[64:65], v163 offset:47168
	ds_read_b64_tr_b16 v[66:67], v163 offset:48704
	ds_read_b64_tr_b16 v[68:69], v163 offset:50240
	ds_read_b64_tr_b16 v[70:71], v163 offset:51776
	ds_read_b64_tr_b16 v[72:73], v163 offset:53312
	ds_read_b64_tr_b16 v[74:75], v163 offset:54848
	ds_read_b64_tr_b16 v[76:77], v163 offset:56384
	ds_read_b64_tr_b16 v[78:79], v163 offset:57920
	s_waitcnt lgkmcnt(12)
	v_mfma_f32_32x32x16_bf16 v[16:31], v[52:55], v[136:139], v[16:31]
	s_waitcnt lgkmcnt(10)
	v_mfma_f32_32x32x16_bf16 v[16:31], v[56:59], v[132:135], v[16:31]
	s_waitcnt lgkmcnt(8)
	v_mfma_f32_32x32x16_bf16 v[16:31], v[60:63], v[128:131], v[16:31]
	s_waitcnt lgkmcnt(6)
	v_mfma_f32_32x32x16_bf16 v[0:15], v[48:51], v[64:67], v[0:15]
	s_waitcnt lgkmcnt(4)
	v_mfma_f32_32x32x16_bf16 v[0:15], v[52:55], v[68:71], v[0:15]
	s_waitcnt lgkmcnt(2)
	v_mfma_f32_32x32x16_bf16 v[0:15], v[56:59], v[72:75], v[0:15]
	s_waitcnt lgkmcnt(0)
	v_mfma_f32_32x32x16_bf16 v[0:15], v[60:63], v[76:79], v[0:15]
	s_andn2_b64 vcc, exec, s[36:37]
	s_cbranch_vccnz .LBB0_593

; #define ATT_LOAD(S, j) do { rk##S = *(const u32x4*)(ksrc + (size_t)(j) * 64 * 1024); if (!DIFF && tid < 256) rk2##S = *(const u32x4*)(k2src + (size_t)(j) * 64 * 32); \
;         rv0##S = *(const u32x4*)(vsrc + (size_t)(j) * 64 * 1024); if (DIFF) rv1##S = *(const u32x4*)(vsrc + (size_t)(j) * 64 * 1024 + 32 * 1024); } while (0)
; #define ATT_STORE(S, bufp) do { *(LAS u32x4*)((bufp) + kdst) = rk##S; if (!DIFF && tid < 256) *(LAS u32x4*)((bufp) + k2dst) = rk2##S; \
;         *(LAS u32x4*)((bufp) + vdst) = rv0##S; if (DIFF) *(LAS u32x4*)((bufp) + vdst + 32 * PV) = rv1##S; } while (0)
; #define ATT_COMPUTE(j, bufp) do { if ((j) < my_nt) { const int kb_ = 64 * (j); const int mode_ = DIFF ? ((kb_ + 63 - qrow0 <= -128) ? 1 : 2) : 0; \
;         attn_tile<DQK, DV, DIFF>(st, (bufp), (bufp) + KB, mode_, tab, kb_ - (qrow0 + q), 64, (j) == 0, wsf, lane); } } while (0)
; template <int DQK, int DV, bool HAS_BIAS>
; __device__ __forceinline__ void attn_tile(AttnState<DQK, DV>& st, const LAS unsigned char* Kt, const LAS unsigned char* Vt, int bias_mode, const LAS float* tab, int rel0, int nkeys, bool first, LAS float* wsf, int lane) {
;     ...
;     float sum0 = 0.f, sum1 = 0.f;
; #pragma unroll
;     for (int r = 0; r < 16; ++r) { p0[r] = __builtin_amdgcn_exp2f(p0[r]); p1[r] = __builtin_amdgcn_exp2f(p1[r]); sum0 += p0[r]; sum1 += p1[r]; }
;     st.l += sum0 + sum1;
;     bf16x8 pf[4];
;     pf[0] = pack8(p0[0], p0[1], p0[2], p0[3], p0[4], p0[5], p0[6], p0[7]);
;     pf[1] = pack8(p0[8], p0[9], p0[10], p0[11], p0[12], p0[13], p0[14], p0[15]);
;     pf[2] = pack8(p1[0], p1[1], p1[2], p1[3], p1[4], p1[5], p1[6], p1[7]);
;     pf[3] = pack8(p1[8], p1[9], p1[10], p1[11], p1[12], p1[13], p1[14], p1[15]);
; template <bool DIFF>
; __device__ __forceinline__ void attn_unit_coop(const Grp& G, int b, int h, int qb, int n, LAS unsigned char* lds, const int tid_in) {
;     ...
;             if (j + 3 < NT) ATT_LOAD(A, j + 3);
;             ATT_COMPUTE(j + 1, b1);
;             if (j + 2 < NT) ATT_STORE(B, b0);
.LBB0_601:
	v_exp_f32_e32 v165, v48
	v_exp_f32_e32 v164, v64
	v_exp_f32_e32 v167, v49
	v_exp_f32_e32 v166, v65
	v_exp_f32_e32 v65, v50
	v_exp_f32_e32 v64, v66
	v_exp_f32_e32 v169, v51
	v_exp_f32_e32 v168, v67
	v_add_f32_e32 v48, 0, v164
	v_add_f32_e32 v49, 0, v165
	v_exp_f32_e32 v67, v52
	v_exp_f32_e32 v66, v68
	v_add_f32_e32 v48, v166, v48
	v_add_f32_e32 v49, v167, v49
	v_exp_f32_e32 v171, v53
	v_exp_f32_e32 v170, v69
	v_add_f32_e32 v48, v64, v48
	v_add_f32_e32 v49, v65, v49
	v_exp_f32_e32 v69, v54
	v_exp_f32_e32 v68, v70
	v_add_f32_e32 v48, v168, v48
	v_add_f32_e32 v49, v169, v49
	v_exp_f32_e32 v173, v55
	v_exp_f32_e32 v172, v71
	v_exp_f32_e32 v71, v56
	v_exp_f32_e32 v70, v72
	v_add_f32_e32 v48, v66, v48
	v_add_f32_e32 v49, v67, v49
	v_exp_f32_e32 v175, v57
	v_exp_f32_e32 v174, v73
	v_add_f32_e32 v48, v170, v48
	v_add_f32_e32 v49, v171, v49
	v_exp_f32_e32 v73, v58
	v_exp_f32_e32 v72, v74
	v_add_f32_e32 v48, v68, v48
	v_add_f32_e32 v49, v69, v49
	v_exp_f32_e32 v177, v59
	v_exp_f32_e32 v176, v75
	v_add_f32_e32 v48, v172, v48
	v_add_f32_e32 v49, v173, v49
	v_exp_f32_e32 v75, v60
	v_exp_f32_e32 v74, v76
	v_add_f32_e32 v48, v70, v48
	v_add_f32_e32 v49, v71, v49
	v_exp_f32_e32 v179, v61
	v_exp_f32_e32 v178, v77
	v_add_f32_e32 v48, v174, v48
	v_add_f32_e32 v49, v175, v49
	v_exp_f32_e32 v77, v62
	v_exp_f32_e32 v76, v78
	v_add_f32_e32 v48, v72, v48
	v_add_f32_e32 v49, v73, v49
	v_exp_f32_e32 v181, v63
	v_exp_f32_e32 v180, v79
	v_add_f32_e32 v48, v176, v48
	v_add_f32_e32 v49, v177, v49
	v_cvt_pk_bf16_f32 v50, v67, v171
	v_add_f32_e32 v48, v74, v48
	v_add_f32_e32 v49, v75, v49
	v_cvt_pk_bf16_f32 v51, v69, v173
	v_add_f32_e32 v48, v178, v48
	v_add_f32_e32 v49, v179, v49
	v_cvt_pk_bf16_f32 v52, v71, v175
	v_add_f32_e32 v48, v76, v48
	v_add_f32_e32 v49, v77, v49
	v_cvt_pk_bf16_f32 v53, v73, v177
	v_add_f32_e32 v48, v180, v48
	v_add_f32_e32 v49, v181, v49
	v_cvt_pk_bf16_f32 v54, v75, v179
	v_add_f32_e32 v48, v48, v49
	v_add_f32_e32 v160, v160, v48
	v_cvt_pk_bf16_f32 v48, v165, v167
	v_cvt_pk_bf16_f32 v49, v65, v169
	v_cvt_pk_bf16_f32 v55, v77, v181
	v_cvt_pk_bf16_f32 v56, v164, v166
	v_cvt_pk_bf16_f32 v57, v64, v168
	v_cvt_pk_bf16_f32 v58, v66, v170
	v_cvt_pk_bf16_f32 v59, v68, v172
	v_cvt_pk_bf16_f32 v60, v70, v174
	v_cvt_pk_bf16_f32 v61, v72, v176
	v_cvt_pk_bf16_f32 v62, v74, v178
	v_cvt_pk_bf16_f32 v63, v76, v180
	s_waitcnt lgkmcnt(6)
	v_mfma_f32_32x32x16_bf16 v[16:31], v[48:51], v[140:143], v[16:31]
	ds_read_b64_tr_b16 v[64:65], v163 offset:21568
	ds_read_b64_tr_b16 v[66:67], v163 offset:23104
	ds_read_b64_tr_b16 v[68:69], v163 offset:24640
	ds_read_b64_tr_b16 v[70:71], v163 offset:26176
	ds_read_b64_tr_b16 v[72:73], v163 offset:27712
	ds_read_b64_tr_b16 v[74:75], v163 offset:29248
	ds_read_b64_tr_b16 v[76:77], v163 offset:30784
	ds_read_b64_tr_b16 v[78:79], v163 offset:32320
	s_waitcnt lgkmcnt(12)
	v_mfma_f32_32x32x16_bf16 v[16:31], v[52:55], v[136:139], v[16:31]
	s_waitcnt lgkmcnt(10)
	v_mfma_f32_32x32x16_bf16 v[16:31], v[56:59], v[132:135], v[16:31]
	s_waitcnt lgkmcnt(8)
	v_mfma_f32_32x32x16_bf16 v[16:31], v[60:63], v[128:131], v[16:31]
	s_waitcnt lgkmcnt(6)
	v_mfma_f32_32x32x16_bf16 v[0:15], v[48:51], v[64:67], v[0:15]
	s_waitcnt lgkmcnt(4)
	v_mfma_f32_32x32x16_bf16 v[0:15], v[52:55], v[68:71], v[0:15]
	s_waitcnt lgkmcnt(2)
	v_mfma_f32_32x32x16_bf16 v[0:15], v[56:59], v[72:75], v[0:15]
	s_waitcnt lgkmcnt(0)
	v_mfma_f32_32x32x16_bf16 v[0:15], v[60:63], v[76:79], v[0:15]
	s_waitcnt vmcnt(1)
	ds_write_b128 v156, v[108:111] offset:33792
	s_and_saveexec_b64 s[4:5], s[0:1]
	s_cbranch_execnz .LBB0_573
	s_branch .LBB0_574
